# attention tile bodies: zero-seeded row-sum add folded into the next add (6 sites, bit-exact)
# speedup vs baseline: 1.0084x; 1.0084x over previous
; #define ALAS __attribute__((address_space(3)))
; __device__ __forceinline__ void anchor(f32x16& s0, f32x16& s1, float& mref) {
;     float ta = __builtin_fmaxf(__builtin_fmaxf(s0[0], s0[1]), s1[0]), tb = __builtin_fmaxf(__builtin_fmaxf(s0[2], s0[3]), s1[1]); ta = __builtin_fmaxf(__builtin_fmaxf(ta, s1[2]), s1[3]);
; #pragma unroll
;     for (int r = 4; r < 16; r += 4) { ta = __builtin_fmaxf(__builtin_fmaxf(ta, s0[r]), s0[r + 1]); tb = __builtin_fmaxf(__builtin_fmaxf(tb, s0[r + 2]), s0[r + 3]);
;         ta = __builtin_fmaxf(__builtin_fmaxf(ta, s1[r]), s1[r + 1]); tb = __builtin_fmaxf(__builtin_fmaxf(tb, s1[r + 2]), s1[r + 3]); }
;     float tm = __builtin_fmaxf(ta, tb);
;     tm = __builtin_fmaxf(tm, __shfl_xor(tm, 32));
;     mref += tm;
; #pragma unroll
;     for (int r = 0; r < 16; ++r) { s0[r] -= tm; s1[r] -= tm; }
; }
; template <int NDB>
; __device__ __forceinline__ void softmax_pv(f32x16& s0, f32x16& s1, float& mref, float& lsum, f32x16 (&o)[NDB], const ALAS unsigned char* Vb, int r32, int hi) {
;     const unsigned vp = (unsigned)(uintptr_t)(Vb + r32 * ROWB + hi * 16);
;     bf16x8 va[2 * NDB], vb[2 * NDB];
;     issue_v<NDB, 0>(va, vp);
;     float ps = 0.f;
; #pragma unroll
;     for (int r = 0; r < 16; ++r) { s0[r] = ex2(s0[r]); ps += s0[r]; }
;     bf16x8 pf0, pf1, pf2, pf3;
;     pack16(s0, pf0, pf1);
;     wait_v<NDB>(va);
;     issue_v<NDB, 1>(vb, vp);
;     __builtin_amdgcn_sched_barrier(0);
; #pragma unroll
;     for (int d = 0; d < NDB; ++d) o[d] = __builtin_amdgcn_mfma_f32_32x32x16_bf16(va[d], pf0, o[d], 0, 0, 0);
; #pragma unroll
;     for (int d = 0; d < NDB; ++d) o[d] = __builtin_amdgcn_mfma_f32_32x32x16_bf16(va[NDB + d], pf1, o[d], 0, 0, 0);
; #pragma unroll
;     for (int r = 0; r < 16; ++r) { s1[r] = ex2(s1[r]); ps += s1[r]; }
;     pack16(s1, pf2, pf3);
; #pragma unroll
;     for (int i = 0; i < 2 * NDB; ++i) { __builtin_amdgcn_sched_group_barrier(0x008, 1, 0); __builtin_amdgcn_sched_group_barrier(0x002, (NDB == 4 ? 5 : 10), 0); }
;     __builtin_amdgcn_sched_barrier(0);
;     wait_v<NDB>(vb);
;     __builtin_amdgcn_sched_barrier(0);
; #pragma unroll
;     for (int d = 0; d < NDB; ++d) o[d] = __builtin_amdgcn_mfma_f32_32x32x16_bf16(vb[d], pf2, o[d], 0, 0, 0);
; #pragma unroll
;     for (int d = 0; d < NDB; ++d) o[d] = __builtin_amdgcn_mfma_f32_32x32x16_bf16(vb[NDB + d], pf3, o[d], 0, 0, 0);
;     lsum += ps;
.LBB0_500:
	s_nop 9
	v_max_f32_e32 v32, v17, v17
	v_max_f32_e32 v33, v16, v16
	v_max_f32_e32 v32, v33, v32
	v_max3_f32 v33, v18, v19, v1
	v_max3_f32 v32, v32, v0, v2
	v_max3_f32 v32, v32, v3, v20
	v_max3_f32 v33, v33, v22, v23
	v_max3_f32 v32, v32, v21, v4
	v_max3_f32 v33, v33, v6, v7
	v_max3_f32 v32, v32, v5, v24
	v_max3_f32 v33, v33, v26, v27
	v_max3_f32 v32, v32, v25, v8
	v_max3_f32 v33, v33, v10, v11
	v_max3_f32 v32, v32, v9, v28
	v_max3_f32 v33, v33, v30, v31
	v_max3_f32 v32, v32, v29, v12
	v_max3_f32 v33, v33, v14, v15
	v_max3_f32 v32, v32, v13, v33
	ds_bpermute_b32 v33, v170, v32
	v_mul_u32_u24_e32 v143, 0x90, v70
	s_waitcnt lgkmcnt(0)
	v_max_f32_e32 v33, v33, v33
	v_max_f32_e32 v69, v32, v33
	v_sub_f32_e32 v68, v0, v69
	v_add_u32_e32 v0, 0, v143
	v_sub_f32_e32 v71, v1, v69
	v_sub_f32_e32 v131, v2, v69
	v_sub_f32_e32 v159, v3, v69
	v_add3_u32 v32, v0, v130, s35
	ds_read_b128 v[0:3], v32 offset:0
	v_sub_f32_e32 v161, v4, v69
	v_sub_f32_e32 v171, v5, v69
	v_sub_f32_e32 v196, v6, v69
	v_sub_f32_e32 v197, v7, v69
	ds_read_b128 v[4:7], v32 offset:4608
	v_sub_f32_e32 v198, v8, v69
	v_sub_f32_e32 v199, v9, v69
	v_sub_f32_e32 v216, v10, v69
	v_sub_f32_e32 v217, v11, v69
	ds_read_b128 v[8:11], v32 offset:9216
	v_sub_f32_e32 v218, v12, v69
	v_sub_f32_e32 v219, v13, v69
	v_sub_f32_e32 v220, v14, v69
	v_sub_f32_e32 v221, v15, v69
	ds_read_b128 v[12:15], v32 offset:13824
	ds_read_b128 v[72:75], v32 offset:32
	ds_read_b128 v[76:79], v32 offset:4640
	ds_read_b128 v[80:83], v32 offset:9248
	ds_read_b128 v[84:87], v32 offset:13856
	v_sub_f32_e32 v16, v16, v69
	s_waitcnt lgkmcnt(0)
	ds_read_b128 v[162:165], v32 offset:64
	ds_read_b128 v[166:169], v32 offset:4672
	ds_read_b128 v[172:175], v32 offset:9280
	ds_read_b128 v[176:179], v32 offset:13888
	ds_read_b128 v[180:183], v32 offset:96
	v_sub_f32_e32 v17, v17, v69
	v_sub_f32_e32 v18, v18, v69
	v_sub_f32_e32 v19, v19, v69
	v_sub_f32_e32 v20, v20, v69
	v_sub_f32_e32 v21, v21, v69
	v_sub_f32_e32 v22, v22, v69
	v_sub_f32_e32 v23, v23, v69
	v_sub_f32_e32 v24, v24, v69
	v_sub_f32_e32 v25, v25, v69
	v_sub_f32_e32 v26, v26, v69
	v_sub_f32_e32 v27, v27, v69
	v_sub_f32_e32 v28, v28, v69
	v_sub_f32_e32 v29, v29, v69
	v_sub_f32_e32 v30, v30, v69
	v_sub_f32_e32 v31, v31, v69
	ds_read_b128 v[184:187], v32 offset:4704
	v_exp_f32_e32 v16, v16
	v_exp_f32_e32 v17, v17
	v_exp_f32_e32 v18, v18
	v_exp_f32_e32 v19, v19
	v_exp_f32_e32 v20, v20
	v_exp_f32_e32 v21, v21
	v_exp_f32_e32 v22, v22
	v_exp_f32_e32 v23, v23
	v_exp_f32_e32 v24, v24
	v_exp_f32_e32 v25, v25
	v_exp_f32_e32 v222, v26
	v_exp_f32_e32 v223, v27
	v_exp_f32_e32 v224, v28
	v_exp_f32_e32 v225, v29
	v_exp_f32_e32 v226, v30
	v_exp_f32_e32 v227, v31
	ds_read_b128 v[188:191], v32 offset:9312
	ds_read_b128 v[192:195], v32 offset:13920
	v_cvt_pk_bf16_f32 v88, v16, v17
	v_cvt_pk_bf16_f32 v89, v18, v19
	v_cvt_pk_bf16_f32 v90, v20, v21
	v_cvt_pk_bf16_f32 v91, v22, v23
	v_cvt_pk_bf16_f32 v92, v24, v25
	v_cvt_pk_bf16_f32 v93, v222, v223
	v_cvt_pk_bf16_f32 v94, v224, v225
	v_cvt_pk_bf16_f32 v95, v226, v227
	v_mfma_f32_32x32x16_bf16 v[48:63], v[0:3], v[88:91], 0
	v_add_f32_e32 v0, v17, v16
	v_add_f32_e32 v0, v18, v0
	v_add_f32_e32 v0, v19, v0
	v_add_f32_e32 v0, v20, v0
	v_exp_f32_e32 v68, v68
	v_exp_f32_e32 v71, v71
	v_mfma_f32_32x32x16_bf16 v[32:47], v[4:7], v[88:91], 0
	v_add_f32_e32 v0, v21, v0
	v_add_f32_e32 v0, v22, v0
	v_add_f32_e32 v0, v23, v0
	v_add_f32_e32 v0, v24, v0
	v_add_f32_e32 v0, v25, v0
	v_exp_f32_e32 v131, v131
	v_exp_f32_e32 v159, v159
	v_mfma_f32_32x32x16_bf16 v[16:31], v[8:11], v[88:91], 0
	v_add_f32_e32 v0, v222, v0
	v_add_f32_e32 v0, v223, v0
	v_add_f32_e32 v0, v224, v0
	v_add_f32_e32 v0, v225, v0
	v_add_f32_e32 v222, v226, v0
	v_exp_f32_e32 v161, v161
	v_exp_f32_e32 v171, v171
	v_mfma_f32_32x32x16_bf16 v[0:15], v[12:15], v[88:91], 0
	v_add_f32_e32 v222, v227, v222
	v_cvt_pk_bf16_f32 v88, v68, v71
	v_add_f32_e32 v68, v68, v222
	v_add_f32_e32 v68, v71, v68
	v_exp_f32_e32 v196, v196
	v_add_f32_e32 v68, v131, v68
	v_exp_f32_e32 v197, v197
	v_exp_f32_e32 v198, v198
	v_exp_f32_e32 v199, v199
	v_exp_f32_e32 v216, v216
	v_exp_f32_e32 v217, v217
	v_exp_f32_e32 v218, v218
	v_exp_f32_e32 v219, v219
	v_exp_f32_e32 v220, v220
	v_exp_f32_e32 v221, v221
	v_add_f32_e32 v68, v159, v68
	v_add_f32_e32 v68, v161, v68
	v_add_f32_e32 v68, v171, v68
	v_add_f32_e32 v68, v196, v68
	v_cvt_pk_bf16_f32 v89, v131, v159
	v_cvt_pk_bf16_f32 v90, v161, v171
	v_cvt_pk_bf16_f32 v91, v196, v197
	v_mfma_f32_32x32x16_bf16 v[48:63], v[72:75], v[92:95], v[48:63]
	v_cvt_pk_bf16_f32 v72, v198, v199
	v_cvt_pk_bf16_f32 v73, v216, v217
	v_cvt_pk_bf16_f32 v74, v218, v219
	v_cvt_pk_bf16_f32 v75, v220, v221
	v_add_f32_e32 v68, v197, v68
	v_add_f32_e32 v68, v198, v68
	v_add_f32_e32 v68, v199, v68
	v_mfma_f32_32x32x16_bf16 v[32:47], v[76:79], v[92:95], v[32:47]
	v_add_f32_e32 v68, v216, v68
	v_add_f32_e32 v68, v217, v68
	v_add_f32_e32 v68, v218, v68
	v_add_f32_e32 v68, v219, v68
	v_add_f32_e32 v68, v220, v68
	v_mfma_f32_32x32x16_bf16 v[16:31], v[80:83], v[92:95], v[16:31]
	v_mfma_f32_32x32x16_bf16 v[0:15], v[84:87], v[92:95], v[0:15]
	s_waitcnt lgkmcnt(0)
	s_nop 0
	v_mfma_f32_32x32x16_bf16 v[48:63], v[162:165], v[88:91], v[48:63]
	v_add_f32_e32 v68, v221, v68
	v_add_f32_e64 v162, v68, 0
	v_add_f32_e64 v163, v69, 0
	v_cmp_lt_f32_e32 vcc, s34, v68
	v_mfma_f32_32x32x16_bf16 v[32:47], v[166:169], v[88:91], v[32:47]
	v_mfma_f32_32x32x16_bf16 v[16:31], v[172:175], v[88:91], v[16:31]
	v_mfma_f32_32x32x16_bf16 v[0:15], v[176:179], v[88:91], v[0:15]
	v_mfma_f32_32x32x16_bf16 v[48:63], v[180:183], v[72:75], v[48:63]
	v_mfma_f32_32x32x16_bf16 v[32:47], v[184:187], v[72:75], v[32:47]
	v_mfma_f32_32x32x16_bf16 v[16:31], v[188:191], v[72:75], v[16:31]
	v_mfma_f32_32x32x16_bf16 v[0:15], v[192:195], v[72:75], v[0:15]
	s_cbranch_vccz .LBB0_502
; __device__ __forceinline__ float ex2(float x) { return __builtin_amdgcn_exp2f(x); }
; template <int NDB>
; __device__ __forceinline__ void softmax_pv(f32x16& s0, f32x16& s1, float& mref, float& lsum, f32x16 (&o)[NDB], const ALAS unsigned char* Vb, int r32, int hi) {
;     ...
;     lsum += ps;
;     if (__any(ps > 1048576.0f)) {
;         const float pt = ps + __shfl_xor(ps, 32); const float dl = pt > 1048576.0f ? floorf(__log2f(pt)) : 0.f, al = ex2(-dl); mref += dl; lsum *= al;
; #pragma unroll
;         for (int d = 0; d < NDB; ++d)
; #pragma unroll
;             for (int r = 0; r < 16; ++r) o[d][r] *= al;
;     }
	ds_bpermute_b32 v69, v170, v68
	s_waitcnt lgkmcnt(0)
	v_add_f32_e32 v68, v68, v69
	v_log_f32_e32 v69, v68
	v_cmp_lt_f32_e32 vcc, s34, v68
	v_floor_f32_e32 v69, v69
	s_nop 0
	v_cndmask_b32_e32 v69, 0, v69, vcc
	v_exp_f32_e64 v68, -v69
	s_nop 0
	v_pk_add_f32 v[72:73], v[162:163], v[68:69]
	v_pk_mul_f32 v[62:63], v[62:63], v[68:69] op_sel_hi:[1,0]
	v_pk_mul_f32 v[60:61], v[60:61], v[68:69] op_sel_hi:[1,0]
	v_pk_mul_f32 v[58:59], v[58:59], v[68:69] op_sel_hi:[1,0]
	v_pk_mul_f32 v[56:57], v[56:57], v[68:69] op_sel_hi:[1,0]
	v_pk_mul_f32 v[54:55], v[54:55], v[68:69] op_sel_hi:[1,0]
	v_pk_mul_f32 v[52:53], v[52:53], v[68:69] op_sel_hi:[1,0]
	v_pk_mul_f32 v[50:51], v[50:51], v[68:69] op_sel_hi:[1,0]
	v_pk_mul_f32 v[48:49], v[48:49], v[68:69] op_sel_hi:[1,0]
	v_pk_mul_f32 v[46:47], v[46:47], v[68:69] op_sel_hi:[1,0]
	v_pk_mul_f32 v[44:45], v[44:45], v[68:69] op_sel_hi:[1,0]
	v_pk_mul_f32 v[42:43], v[42:43], v[68:69] op_sel_hi:[1,0]
	v_pk_mul_f32 v[40:41], v[40:41], v[68:69] op_sel_hi:[1,0]
	v_pk_mul_f32 v[38:39], v[38:39], v[68:69] op_sel_hi:[1,0]
	v_pk_mul_f32 v[36:37], v[36:37], v[68:69] op_sel_hi:[1,0]
	v_pk_mul_f32 v[34:35], v[34:35], v[68:69] op_sel_hi:[1,0]
	v_pk_mul_f32 v[32:33], v[32:33], v[68:69] op_sel_hi:[1,0]
	v_pk_mul_f32 v[30:31], v[30:31], v[68:69] op_sel_hi:[1,0]
	v_pk_mul_f32 v[28:29], v[28:29], v[68:69] op_sel_hi:[1,0]
	v_pk_mul_f32 v[26:27], v[26:27], v[68:69] op_sel_hi:[1,0]
	v_pk_mul_f32 v[24:25], v[24:25], v[68:69] op_sel_hi:[1,0]
	v_pk_mul_f32 v[22:23], v[22:23], v[68:69] op_sel_hi:[1,0]
	v_pk_mul_f32 v[20:21], v[20:21], v[68:69] op_sel_hi:[1,0]
	v_pk_mul_f32 v[18:19], v[18:19], v[68:69] op_sel_hi:[1,0]
	v_pk_mul_f32 v[16:17], v[16:17], v[68:69] op_sel_hi:[1,0]
	v_pk_mul_f32 v[14:15], v[14:15], v[68:69] op_sel_hi:[1,0]
	v_pk_mul_f32 v[12:13], v[12:13], v[68:69] op_sel_hi:[1,0]
	v_pk_mul_f32 v[10:11], v[10:11], v[68:69] op_sel_hi:[1,0]
	v_pk_mul_f32 v[8:9], v[8:9], v[68:69] op_sel_hi:[1,0]
	v_pk_mul_f32 v[6:7], v[6:7], v[68:69] op_sel_hi:[1,0]
	v_pk_mul_f32 v[4:5], v[4:5], v[68:69] op_sel_hi:[1,0]
	v_pk_mul_f32 v[2:3], v[2:3], v[68:69] op_sel_hi:[1,0]
	v_pk_mul_f32 v[0:1], v[0:1], v[68:69] op_sel_hi:[1,0]
	v_mul_f32_e32 v162, v162, v68
	v_mov_b32_e32 v163, v73

; #define ALAS __attribute__((address_space(3)))
; __device__ __forceinline__ float ex2(float x) { return __builtin_amdgcn_exp2f(x); }
; template <int NDB> __device__ __forceinline__ void wait_v(bf16x8 (&v)[2 * NDB]) { if constexpr (NDB == 4) lds_wait8(v); else lds_wait4(v); }
; template <int NDB>
; __device__ __forceinline__ void softmax_pv(f32x16& s0, f32x16& s1, float& mref, float& lsum, f32x16 (&o)[NDB], const ALAS unsigned char* Vb, int r32, int hi) {
;     const unsigned vp = (unsigned)(uintptr_t)(Vb + r32 * ROWB + hi * 16);
;     bf16x8 va[2 * NDB], vb[2 * NDB];
;     issue_v<NDB, 0>(va, vp);
;     float ps = 0.f;
; #pragma unroll
;     for (int r = 0; r < 16; ++r) { s0[r] = ex2(s0[r]); ps += s0[r]; }
;     bf16x8 pf0, pf1, pf2, pf3;
;     pack16(s0, pf0, pf1);
;     wait_v<NDB>(va);
;     issue_v<NDB, 1>(vb, vp);
;     __builtin_amdgcn_sched_barrier(0);
; #pragma unroll
;     for (int d = 0; d < NDB; ++d) o[d] = __builtin_amdgcn_mfma_f32_32x32x16_bf16(va[d], pf0, o[d], 0, 0, 0);
; #pragma unroll
;     for (int d = 0; d < NDB; ++d) o[d] = __builtin_amdgcn_mfma_f32_32x32x16_bf16(va[NDB + d], pf1, o[d], 0, 0, 0);
; #pragma unroll
;     for (int r = 0; r < 16; ++r) { s1[r] = ex2(s1[r]); ps += s1[r]; }
;     pack16(s1, pf2, pf3);
; #pragma unroll
;     for (int i = 0; i < 2 * NDB; ++i) { __builtin_amdgcn_sched_group_barrier(0x008, 1, 0); __builtin_amdgcn_sched_group_barrier(0x002, (NDB == 4 ? 5 : 10), 0); }
;     __builtin_amdgcn_sched_barrier(0);
;     wait_v<NDB>(vb);
;     __builtin_amdgcn_sched_barrier(0);
; #pragma unroll
;     for (int d = 0; d < NDB; ++d) o[d] = __builtin_amdgcn_mfma_f32_32x32x16_bf16(vb[d], pf2, o[d], 0, 0, 0);
; #pragma unroll
;     for (int d = 0; d < NDB; ++d) o[d] = __builtin_amdgcn_mfma_f32_32x32x16_bf16(vb[NDB + d], pf3, o[d], 0, 0, 0);
;     lsum += ps;
;     if (__any(ps > 1048576.0f)) {
;         const float pt = ps + __shfl_xor(ps, 32); const float dl = pt > 1048576.0f ? floorf(__log2f(pt)) : 0.f, al = ex2(-dl); mref += dl; lsum *= al;
; #pragma unroll
;         for (int d = 0; d < NDB; ++d)
; #pragma unroll
;             for (int r = 0; r < 16; ++r) o[d][r] *= al;
;     }
.Ldf_509b:
	ds_read_b128 v[172:175], v147 offset:0
	ds_read_b128 v[176:179], v147 offset:4608
	ds_read_b128 v[180:183], v147 offset:9216
	ds_read_b128 v[184:187], v147 offset:13824
	ds_read_b128 v[188:191], v147 offset:32
	ds_read_b128 v[192:195], v147 offset:4640
	ds_read_b128 v[196:199], v147 offset:9248
	ds_read_b128 v[216:219], v147 offset:13856
	s_nop 7
	v_exp_f32_e32 v248, v88
	v_exp_f32_e32 v249, v89
	v_exp_f32_e32 v250, v90
	v_exp_f32_e32 v251, v91
	ds_read_b128 v[88:91], v147 offset:64
	v_exp_f32_e32 v252, v92
	v_exp_f32_e32 v253, v93
	v_exp_f32_e32 v215, v94
	v_exp_f32_e32 v207, v95
	ds_read_b128 v[92:95], v147 offset:4672
	ds_read_b128 v[220:223], v147 offset:9280
	ds_read_b128 v[224:227], v147 offset:13888
	ds_read_b128 v[228:231], v147 offset:96
	ds_read_b128 v[232:235], v147 offset:4704
	v_exp_f32_e32 v161, v80
	v_exp_f32_e32 v168, v81
	v_exp_f32_e32 v169, v82
	v_exp_f32_e32 v171, v83
	v_exp_f32_e32 v244, v84
	v_exp_f32_e32 v245, v85
	v_exp_f32_e32 v246, v86
	v_exp_f32_e32 v247, v87
	ds_read_b128 v[236:239], v147 offset:9312
	ds_read_b128 v[240:243], v147 offset:13920
	v_cvt_pk_bf16_f32 v80, v161, v168
	v_cvt_pk_bf16_f32 v81, v169, v171
	v_cvt_pk_bf16_f32 v82, v244, v245
	v_cvt_pk_bf16_f32 v83, v246, v247
	v_cvt_pk_bf16_f32 v84, v248, v249
	v_cvt_pk_bf16_f32 v85, v250, v251
	v_cvt_pk_bf16_f32 v86, v252, v253
	v_cvt_pk_bf16_f32 v87, v215, v207
	s_waitcnt lgkmcnt(8)
	v_mfma_f32_32x32x16_bf16 v[48:63], v[172:175], v[80:83], v[48:63]
	v_add_f32_e32 v144, v168, v161
	v_add_f32_e32 v144, v169, v144
	v_add_f32_e32 v144, v171, v144
	v_add_f32_e32 v144, v244, v144
	v_exp_f32_e32 v161, v68
	v_exp_f32_e32 v168, v69
	v_mfma_f32_32x32x16_bf16 v[32:47], v[176:179], v[80:83], v[32:47]
	v_add_f32_e32 v144, v245, v144
	v_add_f32_e32 v144, v246, v144
	v_add_f32_e32 v144, v247, v144
	v_add_f32_e32 v144, v248, v144
	v_add_f32_e32 v144, v249, v144
	v_exp_f32_e32 v169, v70
	v_exp_f32_e32 v171, v71
	v_mfma_f32_32x32x16_bf16 v[16:31], v[180:183], v[80:83], v[16:31]
	v_add_f32_e32 v144, v250, v144
	v_add_f32_e32 v144, v251, v144
	v_add_f32_e32 v144, v252, v144
	v_add_f32_e32 v144, v253, v144
	v_add_f32_e32 v144, v215, v144
	v_exp_f32_e32 v72, v72
	v_exp_f32_e32 v73, v73
	v_mfma_f32_32x32x16_bf16 v[0:15], v[184:187], v[80:83], v[0:15]
	v_exp_f32_e32 v81, v64
	v_exp_f32_e32 v82, v65
	v_exp_f32_e32 v83, v66
	v_add_f32_e32 v80, v207, v144
	v_exp_f32_e32 v144, v67
	v_add_f32_e32 v80, v81, v80
	v_add_f32_e32 v80, v82, v80
	v_exp_f32_e32 v74, v74
	v_exp_f32_e32 v75, v75
	v_exp_f32_e32 v76, v76
	v_exp_f32_e32 v77, v77
	v_exp_f32_e32 v78, v78
	v_exp_f32_e32 v79, v79
	v_add_f32_e32 v80, v83, v80
	v_add_f32_e32 v80, v144, v80
	v_add_f32_e32 v80, v161, v80
	v_add_f32_e32 v80, v168, v80
	v_cvt_pk_bf16_f32 v64, v81, v82
	v_cvt_pk_bf16_f32 v65, v83, v144
	v_cvt_pk_bf16_f32 v66, v161, v168
	v_cvt_pk_bf16_f32 v67, v169, v171
	v_mfma_f32_32x32x16_bf16 v[48:63], v[188:191], v[84:87], v[48:63]
	v_cvt_pk_bf16_f32 v68, v72, v73
	v_cvt_pk_bf16_f32 v69, v74, v75
	v_cvt_pk_bf16_f32 v70, v76, v77
	v_cvt_pk_bf16_f32 v71, v78, v79
	v_add_f32_e32 v80, v169, v80
	v_add_f32_e32 v80, v171, v80
	v_add_f32_e32 v72, v72, v80
	v_mfma_f32_32x32x16_bf16 v[32:47], v[192:195], v[84:87], v[32:47]
	v_add_f32_e32 v72, v73, v72
	v_add_f32_e32 v72, v74, v72
	v_add_f32_e32 v72, v75, v72
	v_add_f32_e32 v72, v76, v72
	v_add_f32_e32 v72, v77, v72
	v_add_f32_e32 v72, v78, v72
	v_mfma_f32_32x32x16_bf16 v[16:31], v[196:199], v[84:87], v[16:31]
	v_mfma_f32_32x32x16_bf16 v[0:15], v[216:219], v[84:87], v[0:15]
	s_waitcnt lgkmcnt(0)
	s_nop 0
	v_mfma_f32_32x32x16_bf16 v[48:63], v[88:91], v[64:67], v[48:63]
	v_mfma_f32_32x32x16_bf16 v[32:47], v[92:95], v[64:67], v[32:47]
	v_mfma_f32_32x32x16_bf16 v[16:31], v[220:223], v[64:67], v[16:31]
	v_mfma_f32_32x32x16_bf16 v[0:15], v[224:227], v[64:67], v[0:15]
	v_add_f32_e32 v64, v79, v72
	v_add_f32_e32 v162, v162, v64
	v_cmp_lt_f32_e32 vcc, s34, v64
	v_mfma_f32_32x32x16_bf16 v[48:63], v[228:231], v[68:71], v[48:63]
	v_mfma_f32_32x32x16_bf16 v[32:47], v[232:235], v[68:71], v[32:47]
	v_mfma_f32_32x32x16_bf16 v[16:31], v[236:239], v[68:71], v[16:31]
	v_mfma_f32_32x32x16_bf16 v[0:15], v[240:243], v[68:71], v[0:15]
	s_cbranch_vccz .Ldf_503b
	ds_bpermute_b32 v65, v170, v64
	s_waitcnt lgkmcnt(0)
	v_add_f32_e32 v64, v64, v65
	v_log_f32_e32 v65, v64
	v_cmp_lt_f32_e32 vcc, s34, v64
	v_floor_f32_e32 v65, v65
	s_nop 0
	v_cndmask_b32_e32 v65, 0, v65, vcc
	v_exp_f32_e64 v64, -v65
	v_add_f32_e32 v163, v163, v65
	v_mul_f32_e32 v162, v162, v64
	v_pk_mul_f32 v[62:63], v[62:63], v[64:65] op_sel_hi:[1,0]
	v_pk_mul_f32 v[60:61], v[60:61], v[64:65] op_sel_hi:[1,0]
	v_pk_mul_f32 v[58:59], v[58:59], v[64:65] op_sel_hi:[1,0]
	v_pk_mul_f32 v[56:57], v[56:57], v[64:65] op_sel_hi:[1,0]
	v_pk_mul_f32 v[54:55], v[54:55], v[64:65] op_sel_hi:[1,0]
	v_pk_mul_f32 v[52:53], v[52:53], v[64:65] op_sel_hi:[1,0]
	v_pk_mul_f32 v[50:51], v[50:51], v[64:65] op_sel_hi:[1,0]
	v_pk_mul_f32 v[48:49], v[48:49], v[64:65] op_sel_hi:[1,0]
	v_pk_mul_f32 v[46:47], v[46:47], v[64:65] op_sel_hi:[1,0]
	v_pk_mul_f32 v[44:45], v[44:45], v[64:65] op_sel_hi:[1,0]
	v_pk_mul_f32 v[42:43], v[42:43], v[64:65] op_sel_hi:[1,0]
	v_pk_mul_f32 v[40:41], v[40:41], v[64:65] op_sel_hi:[1,0]
	v_pk_mul_f32 v[38:39], v[38:39], v[64:65] op_sel_hi:[1,0]
	v_pk_mul_f32 v[36:37], v[36:37], v[64:65] op_sel_hi:[1,0]
	v_pk_mul_f32 v[34:35], v[34:35], v[64:65] op_sel_hi:[1,0]
	v_pk_mul_f32 v[32:33], v[32:33], v[64:65] op_sel_hi:[1,0]
	v_pk_mul_f32 v[30:31], v[30:31], v[64:65] op_sel_hi:[1,0]
	v_pk_mul_f32 v[28:29], v[28:29], v[64:65] op_sel_hi:[1,0]
	v_pk_mul_f32 v[26:27], v[26:27], v[64:65] op_sel_hi:[1,0]
	v_pk_mul_f32 v[24:25], v[24:25], v[64:65] op_sel_hi:[1,0]
	v_pk_mul_f32 v[22:23], v[22:23], v[64:65] op_sel_hi:[1,0]
	v_pk_mul_f32 v[20:21], v[20:21], v[64:65] op_sel_hi:[1,0]
	v_pk_mul_f32 v[18:19], v[18:19], v[64:65] op_sel_hi:[1,0]
	v_pk_mul_f32 v[16:17], v[16:17], v[64:65] op_sel_hi:[1,0]
	v_pk_mul_f32 v[14:15], v[14:15], v[64:65] op_sel_hi:[1,0]
	v_pk_mul_f32 v[12:13], v[12:13], v[64:65] op_sel_hi:[1,0]
	v_pk_mul_f32 v[10:11], v[10:11], v[64:65] op_sel_hi:[1,0]
	v_pk_mul_f32 v[8:9], v[8:9], v[64:65] op_sel_hi:[1,0]
	v_pk_mul_f32 v[6:7], v[6:7], v[64:65] op_sel_hi:[1,0]
	v_pk_mul_f32 v[4:5], v[4:5], v[64:65] op_sel_hi:[1,0]
	v_pk_mul_f32 v[2:3], v[2:3], v[64:65] op_sel_hi:[1,0]
	v_pk_mul_f32 v[0:1], v[0:1], v[64:65] op_sel_hi:[1,0]
	s_branch .Ldf_503b

; #define ALAS __attribute__((address_space(3)))
; __device__ __forceinline__ float ex2(float x) { return __builtin_amdgcn_exp2f(x); }
; template <int NDB> __device__ __forceinline__ void wait_v(bf16x8 (&v)[2 * NDB]) { if constexpr (NDB == 4) lds_wait8(v); else lds_wait4(v); }
; template <int NDB>
; __device__ __forceinline__ void softmax_pv(f32x16& s0, f32x16& s1, float& mref, float& lsum, f32x16 (&o)[NDB], const ALAS unsigned char* Vb, int r32, int hi) {
;     const unsigned vp = (unsigned)(uintptr_t)(Vb + r32 * ROWB + hi * 16);
;     bf16x8 va[2 * NDB], vb[2 * NDB];
;     issue_v<NDB, 0>(va, vp);
;     float ps = 0.f;
; #pragma unroll
;     for (int r = 0; r < 16; ++r) { s0[r] = ex2(s0[r]); ps += s0[r]; }
;     bf16x8 pf0, pf1, pf2, pf3;
;     pack16(s0, pf0, pf1);
;     wait_v<NDB>(va);
;     issue_v<NDB, 1>(vb, vp);
;     __builtin_amdgcn_sched_barrier(0);
; #pragma unroll
;     for (int d = 0; d < NDB; ++d) o[d] = __builtin_amdgcn_mfma_f32_32x32x16_bf16(va[d], pf0, o[d], 0, 0, 0);
; #pragma unroll
;     for (int d = 0; d < NDB; ++d) o[d] = __builtin_amdgcn_mfma_f32_32x32x16_bf16(va[NDB + d], pf1, o[d], 0, 0, 0);
; #pragma unroll
;     for (int r = 0; r < 16; ++r) { s1[r] = ex2(s1[r]); ps += s1[r]; }
;     pack16(s1, pf2, pf3);
; #pragma unroll
;     for (int i = 0; i < 2 * NDB; ++i) { __builtin_amdgcn_sched_group_barrier(0x008, 1, 0); __builtin_amdgcn_sched_group_barrier(0x002, (NDB == 4 ? 5 : 10), 0); }
;     __builtin_amdgcn_sched_barrier(0);
;     wait_v<NDB>(vb);
;     __builtin_amdgcn_sched_barrier(0);
; #pragma unroll
;     for (int d = 0; d < NDB; ++d) o[d] = __builtin_amdgcn_mfma_f32_32x32x16_bf16(vb[d], pf2, o[d], 0, 0, 0);
; #pragma unroll
;     for (int d = 0; d < NDB; ++d) o[d] = __builtin_amdgcn_mfma_f32_32x32x16_bf16(vb[NDB + d], pf3, o[d], 0, 0, 0);
;     lsum += ps;
;     if (__any(ps > 1048576.0f)) {
;         const float pt = ps + __shfl_xor(ps, 32); const float dl = pt > 1048576.0f ? floorf(__log2f(pt)) : 0.f, al = ex2(-dl); mref += dl; lsum *= al;
; #pragma unroll
;         for (int d = 0; d < NDB; ++d)
; #pragma unroll
;             for (int r = 0; r < 16; ++r) o[d][r] *= al;
;     }
.LBB0_509:
	ds_read_b128 v[172:175], v147 offset:36864
	ds_read_b128 v[176:179], v147 offset:41472
	ds_read_b128 v[180:183], v147 offset:46080
	ds_read_b128 v[184:187], v147 offset:50688
	ds_read_b128 v[188:191], v147 offset:36896
	ds_read_b128 v[192:195], v147 offset:41504
	ds_read_b128 v[196:199], v147 offset:46112
	ds_read_b128 v[216:219], v147 offset:50720
	s_nop 7
	v_exp_f32_e32 v248, v88
	v_exp_f32_e32 v249, v89
	v_exp_f32_e32 v250, v90
	v_exp_f32_e32 v251, v91
	ds_read_b128 v[88:91], v147 offset:36928
	v_exp_f32_e32 v252, v92
	v_exp_f32_e32 v253, v93
	v_exp_f32_e32 v215, v94
	v_exp_f32_e32 v207, v95
	ds_read_b128 v[92:95], v147 offset:41536
	ds_read_b128 v[220:223], v147 offset:46144
	ds_read_b128 v[224:227], v147 offset:50752
	ds_read_b128 v[228:231], v147 offset:36960
	ds_read_b128 v[232:235], v147 offset:41568
	v_exp_f32_e32 v161, v80
	v_exp_f32_e32 v168, v81
	v_exp_f32_e32 v169, v82
	v_exp_f32_e32 v171, v83
	v_exp_f32_e32 v244, v84
	v_exp_f32_e32 v245, v85
	v_exp_f32_e32 v246, v86
	v_exp_f32_e32 v247, v87
	ds_read_b128 v[236:239], v147 offset:46176
	ds_read_b128 v[240:243], v147 offset:50784
	v_cvt_pk_bf16_f32 v80, v161, v168
	v_cvt_pk_bf16_f32 v81, v169, v171
	v_cvt_pk_bf16_f32 v82, v244, v245
	v_cvt_pk_bf16_f32 v83, v246, v247
	v_cvt_pk_bf16_f32 v84, v248, v249
	v_cvt_pk_bf16_f32 v85, v250, v251
	v_cvt_pk_bf16_f32 v86, v252, v253
	v_cvt_pk_bf16_f32 v87, v215, v207
	s_waitcnt lgkmcnt(8)
	v_mfma_f32_32x32x16_bf16 v[48:63], v[172:175], v[80:83], v[48:63]
	v_add_f32_e32 v144, v168, v161
	v_add_f32_e32 v144, v169, v144
	v_add_f32_e32 v144, v171, v144
	v_add_f32_e32 v144, v244, v144
	v_exp_f32_e32 v161, v68
	v_exp_f32_e32 v168, v69
	v_mfma_f32_32x32x16_bf16 v[32:47], v[176:179], v[80:83], v[32:47]
	v_add_f32_e32 v144, v245, v144
	v_add_f32_e32 v144, v246, v144
	v_add_f32_e32 v144, v247, v144
	v_add_f32_e32 v144, v248, v144
	v_add_f32_e32 v144, v249, v144
	v_exp_f32_e32 v169, v70
	v_exp_f32_e32 v171, v71
	v_mfma_f32_32x32x16_bf16 v[16:31], v[180:183], v[80:83], v[16:31]
	v_add_f32_e32 v144, v250, v144
	v_add_f32_e32 v144, v251, v144
	v_add_f32_e32 v144, v252, v144
	v_add_f32_e32 v144, v253, v144
	v_add_f32_e32 v144, v215, v144
	v_exp_f32_e32 v72, v72
	v_exp_f32_e32 v73, v73
	v_mfma_f32_32x32x16_bf16 v[0:15], v[184:187], v[80:83], v[0:15]
	v_exp_f32_e32 v81, v64
	v_exp_f32_e32 v82, v65
	v_exp_f32_e32 v83, v66
	v_add_f32_e32 v80, v207, v144
	v_exp_f32_e32 v144, v67
	v_add_f32_e32 v80, v81, v80
	v_add_f32_e32 v80, v82, v80
	v_exp_f32_e32 v74, v74
	v_exp_f32_e32 v75, v75
	v_exp_f32_e32 v76, v76
	v_exp_f32_e32 v77, v77
	v_exp_f32_e32 v78, v78
	v_exp_f32_e32 v79, v79
	v_add_f32_e32 v80, v83, v80
	v_add_f32_e32 v80, v144, v80
	v_add_f32_e32 v80, v161, v80
	v_add_f32_e32 v80, v168, v80
	v_cvt_pk_bf16_f32 v64, v81, v82
	v_cvt_pk_bf16_f32 v65, v83, v144
	v_cvt_pk_bf16_f32 v66, v161, v168
	v_cvt_pk_bf16_f32 v67, v169, v171
	v_mfma_f32_32x32x16_bf16 v[48:63], v[188:191], v[84:87], v[48:63]
	v_cvt_pk_bf16_f32 v68, v72, v73
	v_cvt_pk_bf16_f32 v69, v74, v75
	v_cvt_pk_bf16_f32 v70, v76, v77
	v_cvt_pk_bf16_f32 v71, v78, v79
	v_add_f32_e32 v80, v169, v80
	v_add_f32_e32 v80, v171, v80
	v_add_f32_e32 v72, v72, v80
	v_mfma_f32_32x32x16_bf16 v[32:47], v[192:195], v[84:87], v[32:47]
	v_add_f32_e32 v72, v73, v72
	v_add_f32_e32 v72, v74, v72
	v_add_f32_e32 v72, v75, v72
	v_add_f32_e32 v72, v76, v72
	v_add_f32_e32 v72, v77, v72
	v_add_f32_e32 v72, v78, v72
	v_mfma_f32_32x32x16_bf16 v[16:31], v[196:199], v[84:87], v[16:31]
	v_mfma_f32_32x32x16_bf16 v[0:15], v[216:219], v[84:87], v[0:15]
	s_waitcnt lgkmcnt(0)
	s_nop 0
	v_mfma_f32_32x32x16_bf16 v[48:63], v[88:91], v[64:67], v[48:63]
	v_mfma_f32_32x32x16_bf16 v[32:47], v[92:95], v[64:67], v[32:47]
	v_mfma_f32_32x32x16_bf16 v[16:31], v[220:223], v[64:67], v[16:31]
	v_mfma_f32_32x32x16_bf16 v[0:15], v[224:227], v[64:67], v[0:15]
	v_add_f32_e32 v64, v79, v72
	v_add_f32_e32 v162, v162, v64
	v_cmp_lt_f32_e32 vcc, s34, v64
	v_mfma_f32_32x32x16_bf16 v[48:63], v[228:231], v[68:71], v[48:63]
	v_mfma_f32_32x32x16_bf16 v[32:47], v[232:235], v[68:71], v[32:47]
	v_mfma_f32_32x32x16_bf16 v[16:31], v[236:239], v[68:71], v[16:31]
	v_mfma_f32_32x32x16_bf16 v[0:15], v[240:243], v[68:71], v[0:15]
	s_cbranch_vccz .LBB0_503
	ds_bpermute_b32 v65, v170, v64
	s_waitcnt lgkmcnt(0)
	v_add_f32_e32 v64, v64, v65
	v_log_f32_e32 v65, v64
	v_cmp_lt_f32_e32 vcc, s34, v64
	v_floor_f32_e32 v65, v65
	s_nop 0
	v_cndmask_b32_e32 v65, 0, v65, vcc
	v_exp_f32_e64 v64, -v65
	v_add_f32_e32 v163, v163, v65
	v_mul_f32_e32 v162, v162, v64
	v_pk_mul_f32 v[62:63], v[62:63], v[64:65] op_sel_hi:[1,0]
	v_pk_mul_f32 v[60:61], v[60:61], v[64:65] op_sel_hi:[1,0]
	v_pk_mul_f32 v[58:59], v[58:59], v[64:65] op_sel_hi:[1,0]
	v_pk_mul_f32 v[56:57], v[56:57], v[64:65] op_sel_hi:[1,0]
	v_pk_mul_f32 v[54:55], v[54:55], v[64:65] op_sel_hi:[1,0]
	v_pk_mul_f32 v[52:53], v[52:53], v[64:65] op_sel_hi:[1,0]
	v_pk_mul_f32 v[50:51], v[50:51], v[64:65] op_sel_hi:[1,0]
	v_pk_mul_f32 v[48:49], v[48:49], v[64:65] op_sel_hi:[1,0]
	v_pk_mul_f32 v[46:47], v[46:47], v[64:65] op_sel_hi:[1,0]
	v_pk_mul_f32 v[44:45], v[44:45], v[64:65] op_sel_hi:[1,0]
	v_pk_mul_f32 v[42:43], v[42:43], v[64:65] op_sel_hi:[1,0]
	v_pk_mul_f32 v[40:41], v[40:41], v[64:65] op_sel_hi:[1,0]
	v_pk_mul_f32 v[38:39], v[38:39], v[64:65] op_sel_hi:[1,0]
	v_pk_mul_f32 v[36:37], v[36:37], v[64:65] op_sel_hi:[1,0]
	v_pk_mul_f32 v[34:35], v[34:35], v[64:65] op_sel_hi:[1,0]
	v_pk_mul_f32 v[32:33], v[32:33], v[64:65] op_sel_hi:[1,0]
	v_pk_mul_f32 v[30:31], v[30:31], v[64:65] op_sel_hi:[1,0]
	v_pk_mul_f32 v[28:29], v[28:29], v[64:65] op_sel_hi:[1,0]
	v_pk_mul_f32 v[26:27], v[26:27], v[64:65] op_sel_hi:[1,0]
	v_pk_mul_f32 v[24:25], v[24:25], v[64:65] op_sel_hi:[1,0]
	v_pk_mul_f32 v[22:23], v[22:23], v[64:65] op_sel_hi:[1,0]
	v_pk_mul_f32 v[20:21], v[20:21], v[64:65] op_sel_hi:[1,0]
	v_pk_mul_f32 v[18:19], v[18:19], v[64:65] op_sel_hi:[1,0]
	v_pk_mul_f32 v[16:17], v[16:17], v[64:65] op_sel_hi:[1,0]
	v_pk_mul_f32 v[14:15], v[14:15], v[64:65] op_sel_hi:[1,0]
	v_pk_mul_f32 v[12:13], v[12:13], v[64:65] op_sel_hi:[1,0]
	v_pk_mul_f32 v[10:11], v[10:11], v[64:65] op_sel_hi:[1,0]
	v_pk_mul_f32 v[8:9], v[8:9], v[64:65] op_sel_hi:[1,0]
	v_pk_mul_f32 v[6:7], v[6:7], v[64:65] op_sel_hi:[1,0]
	v_pk_mul_f32 v[4:5], v[4:5], v[64:65] op_sel_hi:[1,0]
	v_pk_mul_f32 v[2:3], v[2:3], v[64:65] op_sel_hi:[1,0]
	v_pk_mul_f32 v[0:1], v[0:1], v[64:65] op_sel_hi:[1,0]
	s_branch .LBB0_503

; #define ALAS __attribute__((address_space(3)))
; __device__ __forceinline__ void anchor(f32x16& s0, f32x16& s1, float& mref) {
;     float ta = __builtin_fmaxf(__builtin_fmaxf(s0[0], s0[1]), s1[0]), tb = __builtin_fmaxf(__builtin_fmaxf(s0[2], s0[3]), s1[1]); ta = __builtin_fmaxf(__builtin_fmaxf(ta, s1[2]), s1[3]);
; #pragma unroll
;     for (int r = 4; r < 16; r += 4) { ta = __builtin_fmaxf(__builtin_fmaxf(ta, s0[r]), s0[r + 1]); tb = __builtin_fmaxf(__builtin_fmaxf(tb, s0[r + 2]), s0[r + 3]);
;         ta = __builtin_fmaxf(__builtin_fmaxf(ta, s1[r]), s1[r + 1]); tb = __builtin_fmaxf(__builtin_fmaxf(tb, s1[r + 2]), s1[r + 3]); }
;     float tm = __builtin_fmaxf(ta, tb);
;     tm = __builtin_fmaxf(tm, __shfl_xor(tm, 32));
;     mref += tm;
; #pragma unroll
;     for (int r = 0; r < 16; ++r) { s0[r] -= tm; s1[r] -= tm; }
; }
; template <int NDB>
; __device__ __forceinline__ void softmax_pv(f32x16& s0, f32x16& s1, float& mref, float& lsum, f32x16 (&o)[NDB], const ALAS unsigned char* Vb, int r32, int hi) {
;     const unsigned vp = (unsigned)(uintptr_t)(Vb + r32 * ROWB + hi * 16);
;     bf16x8 va[2 * NDB], vb[2 * NDB];
;     issue_v<NDB, 0>(va, vp);
;     float ps = 0.f;
; #pragma unroll
;     for (int r = 0; r < 16; ++r) { s0[r] = ex2(s0[r]); ps += s0[r]; }
;     bf16x8 pf0, pf1, pf2, pf3;
;     pack16(s0, pf0, pf1);
;     wait_v<NDB>(va);
;     issue_v<NDB, 1>(vb, vp);
;     __builtin_amdgcn_sched_barrier(0);
; #pragma unroll
;     for (int d = 0; d < NDB; ++d) o[d] = __builtin_amdgcn_mfma_f32_32x32x16_bf16(va[d], pf0, o[d], 0, 0, 0);
; #pragma unroll
;     for (int d = 0; d < NDB; ++d) o[d] = __builtin_amdgcn_mfma_f32_32x32x16_bf16(va[NDB + d], pf1, o[d], 0, 0, 0);
; #pragma unroll
;     for (int r = 0; r < 16; ++r) { s1[r] = ex2(s1[r]); ps += s1[r]; }
;     pack16(s1, pf2, pf3);
; #pragma unroll
;     for (int i = 0; i < 2 * NDB; ++i) { __builtin_amdgcn_sched_group_barrier(0x008, 1, 0); __builtin_amdgcn_sched_group_barrier(0x002, (NDB == 4 ? 5 : 10), 0); }
;     __builtin_amdgcn_sched_barrier(0);
;     wait_v<NDB>(vb);
;     __builtin_amdgcn_sched_barrier(0);
; #pragma unroll
;     for (int d = 0; d < NDB; ++d) o[d] = __builtin_amdgcn_mfma_f32_32x32x16_bf16(vb[d], pf2, o[d], 0, 0, 0);
; #pragma unroll
;     for (int d = 0; d < NDB; ++d) o[d] = __builtin_amdgcn_mfma_f32_32x32x16_bf16(vb[NDB + d], pf3, o[d], 0, 0, 0);
;     lsum += ps;
.LBB0_528:
	s_nop 9
	v_max_f32_e32 v40, v17, v17
	v_max_f32_e32 v41, v16, v16
	v_max_f32_e32 v40, v41, v40
	v_max3_f32 v41, v18, v19, v1
	v_max3_f32 v40, v40, v0, v2
	v_max3_f32 v40, v40, v3, v20
	v_max3_f32 v41, v41, v22, v23
	v_max3_f32 v40, v40, v21, v4
	v_max3_f32 v41, v41, v6, v7
	v_max3_f32 v40, v40, v5, v24
	v_max3_f32 v41, v41, v26, v27
	v_max3_f32 v40, v40, v25, v8
	v_max3_f32 v41, v41, v10, v11
	v_max3_f32 v40, v40, v9, v28
	v_max3_f32 v41, v41, v30, v31
	v_max3_f32 v40, v40, v29, v12
	v_max3_f32 v41, v41, v14, v15
	v_max3_f32 v40, v40, v13, v41
	ds_bpermute_b32 v41, v93, v40
	s_waitcnt lgkmcnt(0)
	v_max_f32_e32 v41, v41, v41
	v_max_f32_e32 v41, v40, v41
	v_sub_f32_e32 v40, v0, v41
	v_add_u32_e32 v0, 0, v106
	v_sub_f32_e32 v51, v1, v41
	v_sub_f32_e32 v91, v2, v41
	v_sub_f32_e32 v107, v3, v41
	v_sub_f32_e32 v124, v8, v41
	v_sub_f32_e32 v8, v16, v41
	v_sub_f32_e32 v16, v24, v41
	v_add3_u32 v24, v0, v144, s95
	ds_read_b128 v[0:3], v24 offset:0
	v_sub_f32_e32 v120, v4, v41
	v_sub_f32_e32 v121, v5, v41
	v_sub_f32_e32 v122, v6, v41
	v_sub_f32_e32 v123, v7, v41
	ds_read_b128 v[4:7], v24 offset:4608
	ds_read_b128 v[52:55], v24 offset:32
	ds_read_b128 v[56:59], v24 offset:4640
	v_sub_f32_e32 v125, v9, v41
	s_waitcnt lgkmcnt(0)
	v_sub_f32_e32 v126, v10, v41
	v_sub_f32_e32 v127, v11, v41
	v_sub_f32_e32 v128, v12, v41
	v_sub_f32_e32 v129, v13, v41
	v_sub_f32_e32 v130, v14, v41
	v_sub_f32_e32 v131, v15, v41
	v_sub_f32_e32 v9, v17, v41
	v_sub_f32_e32 v10, v18, v41
	v_sub_f32_e32 v11, v19, v41
	v_sub_f32_e32 v12, v20, v41
	v_sub_f32_e32 v13, v21, v41
	v_sub_f32_e32 v14, v22, v41
	v_sub_f32_e32 v15, v23, v41
	ds_read_b128 v[100:103], v24 offset:64
	v_sub_f32_e32 v17, v25, v41
	v_sub_f32_e32 v18, v26, v41
	v_sub_f32_e32 v19, v27, v41
	v_sub_f32_e32 v20, v28, v41
	v_sub_f32_e32 v21, v29, v41
	v_sub_f32_e32 v22, v30, v41
	v_sub_f32_e32 v23, v31, v41
	v_exp_f32_e32 v132, v8
	v_exp_f32_e32 v133, v9
	v_exp_f32_e32 v134, v10
	v_exp_f32_e32 v135, v11
	v_exp_f32_e32 v12, v12
	v_exp_f32_e32 v13, v13
	v_exp_f32_e32 v14, v14
	v_exp_f32_e32 v15, v15
	ds_read_b128 v[108:111], v24 offset:4672
	v_exp_f32_e32 v136, v16
	v_exp_f32_e32 v137, v17
	v_exp_f32_e32 v138, v18
	v_exp_f32_e32 v139, v19
	v_exp_f32_e32 v140, v20
	v_exp_f32_e32 v141, v21
	v_exp_f32_e32 v142, v22
	v_exp_f32_e32 v143, v23
	ds_read_b128 v[112:115], v24 offset:96
	ds_read_b128 v[116:119], v24 offset:4704
	v_cvt_pk_bf16_f32 v8, v132, v133
	v_cvt_pk_bf16_f32 v9, v134, v135
	v_cvt_pk_bf16_f32 v10, v12, v13
	v_cvt_pk_bf16_f32 v11, v14, v15
	v_cvt_pk_bf16_f32 v60, v136, v137
	v_cvt_pk_bf16_f32 v61, v138, v139
	v_cvt_pk_bf16_f32 v62, v140, v141
	v_cvt_pk_bf16_f32 v63, v142, v143
	v_mfma_f32_32x32x16_bf16 v[16:31], v[0:3], v[8:11], 0
	v_add_f32_e32 v0, v133, v132
	v_add_f32_e32 v0, v134, v0
	v_add_f32_e32 v0, v135, v0
	v_add_f32_e32 v0, v12, v0
	v_add_f32_e32 v0, v13, v0
	v_add_f32_e32 v0, v14, v0
	v_add_f32_e32 v0, v15, v0
	v_add_f32_e32 v0, v136, v0
	v_add_f32_e32 v132, v137, v0
	v_mfma_f32_32x32x16_bf16 v[0:15], v[4:7], v[8:11], 0
	v_add_f32_e32 v132, v138, v132
	v_add_f32_e32 v132, v139, v132
	v_add_f32_e32 v132, v140, v132
	v_exp_f32_e32 v40, v40
	v_exp_f32_e32 v51, v51
	v_add_f32_e32 v132, v141, v132
	v_add_f32_e32 v132, v142, v132
	v_exp_f32_e32 v91, v91
	v_add_f32_e32 v132, v143, v132
	v_exp_f32_e32 v107, v107
	v_exp_f32_e32 v133, v120
	v_cvt_pk_bf16_f32 v120, v40, v51
	v_add_f32_e32 v40, v40, v132
	v_exp_f32_e32 v134, v121
	v_add_f32_e32 v40, v51, v40
	v_exp_f32_e32 v135, v122
	v_add_f32_e32 v40, v91, v40
	v_exp_f32_e32 v136, v123
	v_exp_f32_e32 v124, v124
	v_exp_f32_e32 v125, v125
	v_exp_f32_e32 v126, v126
	v_exp_f32_e32 v127, v127
	v_exp_f32_e32 v128, v128
	v_exp_f32_e32 v129, v129
	v_exp_f32_e32 v130, v130
	v_exp_f32_e32 v131, v131
	v_add_f32_e32 v40, v107, v40
	v_add_f32_e32 v40, v133, v40
	v_add_f32_e32 v40, v134, v40
	v_add_f32_e32 v40, v135, v40
	v_cvt_pk_bf16_f32 v121, v91, v107
	v_cvt_pk_bf16_f32 v122, v133, v134
	v_cvt_pk_bf16_f32 v123, v135, v136
	v_mfma_f32_32x32x16_bf16 v[16:31], v[52:55], v[60:63], v[16:31]
	v_cvt_pk_bf16_f32 v52, v124, v125
	v_cvt_pk_bf16_f32 v53, v126, v127
	v_cvt_pk_bf16_f32 v54, v128, v129
	v_cvt_pk_bf16_f32 v55, v130, v131
	v_add_f32_e32 v40, v136, v40
	v_add_f32_e32 v40, v124, v40
	v_add_f32_e32 v40, v125, v40
	v_mfma_f32_32x32x16_bf16 v[0:15], v[56:59], v[60:63], v[0:15]
	v_add_f32_e32 v40, v126, v40
	v_add_f32_e32 v40, v127, v40
	v_add_f32_e32 v40, v128, v40
	v_add_f32_e32 v40, v129, v40
	v_add_f32_e32 v40, v130, v40
	s_waitcnt lgkmcnt(0)
	s_nop 0
	v_mfma_f32_32x32x16_bf16 v[16:31], v[100:103], v[120:123], v[16:31]
	v_add_f32_e32 v40, v131, v40
	v_add_f32_e64 v100, v40, 0
	v_add_f32_e64 v101, v41, 0
	v_cmp_lt_f32_e32 vcc, s34, v40
	v_mfma_f32_32x32x16_bf16 v[0:15], v[108:111], v[120:123], v[0:15]
	v_mfma_f32_32x32x16_bf16 v[16:31], v[112:115], v[52:55], v[16:31]
	v_mfma_f32_32x32x16_bf16 v[0:15], v[116:119], v[52:55], v[0:15]
	s_cbranch_vccz .LBB0_531
	ds_bpermute_b32 v41, v93, v40
	s_waitcnt lgkmcnt(0)
	v_add_f32_e32 v40, v40, v41
	v_log_f32_e32 v41, v40
	v_cmp_lt_f32_e32 vcc, s34, v40
	v_floor_f32_e32 v41, v41
	s_nop 0
	v_cndmask_b32_e32 v41, 0, v41, vcc
	v_exp_f32_e64 v40, -v41
	s_nop 0
	v_pk_add_f32 v[52:53], v[100:101], v[40:41]
	v_pk_mul_f32 v[30:31], v[30:31], v[40:41] op_sel_hi:[1,0]
	v_pk_mul_f32 v[28:29], v[28:29], v[40:41] op_sel_hi:[1,0]
	v_pk_mul_f32 v[26:27], v[26:27], v[40:41] op_sel_hi:[1,0]
	v_pk_mul_f32 v[24:25], v[24:25], v[40:41] op_sel_hi:[1,0]
	v_pk_mul_f32 v[22:23], v[22:23], v[40:41] op_sel_hi:[1,0]
	v_pk_mul_f32 v[20:21], v[20:21], v[40:41] op_sel_hi:[1,0]
	v_pk_mul_f32 v[18:19], v[18:19], v[40:41] op_sel_hi:[1,0]
	v_pk_mul_f32 v[16:17], v[16:17], v[40:41] op_sel_hi:[1,0]
	v_pk_mul_f32 v[14:15], v[14:15], v[40:41] op_sel_hi:[1,0]
	v_pk_mul_f32 v[12:13], v[12:13], v[40:41] op_sel_hi:[1,0]
	v_pk_mul_f32 v[10:11], v[10:11], v[40:41] op_sel_hi:[1,0]
	v_pk_mul_f32 v[8:9], v[8:9], v[40:41] op_sel_hi:[1,0]
	v_pk_mul_f32 v[6:7], v[6:7], v[40:41] op_sel_hi:[1,0]
	v_pk_mul_f32 v[4:5], v[4:5], v[40:41] op_sel_hi:[1,0]
	v_pk_mul_f32 v[2:3], v[2:3], v[40:41] op_sel_hi:[1,0]
	v_pk_mul_f32 v[0:1], v[0:1], v[40:41] op_sel_hi:[1,0]
	v_mul_f32_e32 v100, v100, v40
	v_mov_b32_e32 v101, v53
	s_branch .LBB0_531

; #define ALAS __attribute__((address_space(3)))
; __device__ __forceinline__ float ex2(float x) { return __builtin_amdgcn_exp2f(x); }
; template <int NDB> __device__ __forceinline__ void wait_v(bf16x8 (&v)[2 * NDB]) { if constexpr (NDB == 4) lds_wait8(v); else lds_wait4(v); }
; template <int NDB>
; __device__ __forceinline__ void softmax_pv(f32x16& s0, f32x16& s1, float& mref, float& lsum, f32x16 (&o)[NDB], const ALAS unsigned char* Vb, int r32, int hi) {
;     const unsigned vp = (unsigned)(uintptr_t)(Vb + r32 * ROWB + hi * 16);
;     bf16x8 va[2 * NDB], vb[2 * NDB];
;     issue_v<NDB, 0>(va, vp);
;     float ps = 0.f;
; #pragma unroll
;     for (int r = 0; r < 16; ++r) { s0[r] = ex2(s0[r]); ps += s0[r]; }
;     bf16x8 pf0, pf1, pf2, pf3;
;     pack16(s0, pf0, pf1);
;     wait_v<NDB>(va);
;     issue_v<NDB, 1>(vb, vp);
;     __builtin_amdgcn_sched_barrier(0);
; #pragma unroll
;     for (int d = 0; d < NDB; ++d) o[d] = __builtin_amdgcn_mfma_f32_32x32x16_bf16(va[d], pf0, o[d], 0, 0, 0);
; #pragma unroll
;     for (int d = 0; d < NDB; ++d) o[d] = __builtin_amdgcn_mfma_f32_32x32x16_bf16(va[NDB + d], pf1, o[d], 0, 0, 0);
; #pragma unroll
;     for (int r = 0; r < 16; ++r) { s1[r] = ex2(s1[r]); ps += s1[r]; }
;     pack16(s1, pf2, pf3);
; #pragma unroll
;     for (int i = 0; i < 2 * NDB; ++i) { __builtin_amdgcn_sched_group_barrier(0x008, 1, 0); __builtin_amdgcn_sched_group_barrier(0x002, (NDB == 4 ? 5 : 10), 0); }
;     __builtin_amdgcn_sched_barrier(0);
;     wait_v<NDB>(vb);
;     __builtin_amdgcn_sched_barrier(0);
; #pragma unroll
;     for (int d = 0; d < NDB; ++d) o[d] = __builtin_amdgcn_mfma_f32_32x32x16_bf16(vb[d], pf2, o[d], 0, 0, 0);
; #pragma unroll
;     for (int d = 0; d < NDB; ++d) o[d] = __builtin_amdgcn_mfma_f32_32x32x16_bf16(vb[NDB + d], pf3, o[d], 0, 0, 0);
;     lsum += ps;
;     if (__any(ps > 1048576.0f)) {
;         const float pt = ps + __shfl_xor(ps, 32); const float dl = pt > 1048576.0f ? floorf(__log2f(pt)) : 0.f, al = ex2(-dl); mref += dl; lsum *= al;
; #pragma unroll
;         for (int d = 0; d < NDB; ++d)
; #pragma unroll
;             for (int r = 0; r < 16; ++r) o[d][r] *= al;
;     }
.Lmb_544b:
	v_add_u32_e32 v102, s17, v106
	v_add3_u32 v102, v102, v144, s95
	ds_read_b128 v[108:111], v102 offset:0
	ds_read_b128 v[112:115], v102 offset:4608
	ds_read_b128 v[116:119], v102 offset:32
	ds_read_b128 v[120:123], v102 offset:4640
	s_nop 7
	v_exp_f32_e32 v139, v56
	v_exp_f32_e32 v140, v57
	v_exp_f32_e32 v141, v58
	v_exp_f32_e32 v142, v59
	ds_read_b128 v[56:59], v102 offset:64
	v_exp_f32_e32 v143, v60
	v_exp_f32_e32 v156, v61
	v_exp_f32_e32 v157, v62
	v_exp_f32_e32 v158, v63
	ds_read_b128 v[60:63], v102 offset:4672
	v_exp_f32_e32 v103, v48
	v_exp_f32_e32 v132, v49
	v_exp_f32_e32 v133, v50
	v_exp_f32_e32 v134, v51
	v_exp_f32_e32 v135, v52
	v_exp_f32_e32 v136, v53
	v_exp_f32_e32 v137, v54
	v_exp_f32_e32 v138, v55
	ds_read_b128 v[124:127], v102 offset:96
	ds_read_b128 v[128:131], v102 offset:4704
	v_cvt_pk_bf16_f32 v48, v103, v132
	v_cvt_pk_bf16_f32 v49, v133, v134
	v_cvt_pk_bf16_f32 v50, v135, v136
	v_cvt_pk_bf16_f32 v51, v137, v138
	v_cvt_pk_bf16_f32 v52, v139, v140
	v_cvt_pk_bf16_f32 v53, v141, v142
	v_cvt_pk_bf16_f32 v54, v143, v156
	v_cvt_pk_bf16_f32 v55, v157, v158
	s_waitcnt lgkmcnt(4)
	v_mfma_f32_32x32x16_bf16 v[16:31], v[108:111], v[48:51], v[16:31]
	v_add_f32_e32 v102, v132, v103
	v_add_f32_e32 v102, v133, v102
	v_add_f32_e32 v102, v134, v102
	v_add_f32_e32 v102, v135, v102
	v_add_f32_e32 v102, v136, v102
	v_add_f32_e32 v102, v137, v102
	v_add_f32_e32 v102, v138, v102
	v_add_f32_e32 v102, v139, v102
	v_add_f32_e32 v102, v140, v102
	v_mfma_f32_32x32x16_bf16 v[0:15], v[112:115], v[48:51], v[0:15]
	v_add_f32_e32 v48, v141, v102
	v_add_f32_e32 v48, v142, v48
	v_add_f32_e32 v48, v143, v48
	v_exp_f32_e32 v49, v32
	v_add_f32_e32 v48, v156, v48
	v_exp_f32_e32 v50, v33
	v_add_f32_e32 v48, v157, v48
	v_exp_f32_e32 v51, v34
	v_add_f32_e32 v48, v158, v48
	v_exp_f32_e32 v102, v35
	v_exp_f32_e32 v103, v36
	v_add_f32_e32 v48, v49, v48
	v_exp_f32_e32 v108, v37
	v_add_f32_e32 v48, v50, v48
	v_exp_f32_e32 v109, v38
	v_exp_f32_e32 v110, v39
	v_exp_f32_e32 v40, v40
	v_exp_f32_e32 v41, v41
	v_exp_f32_e32 v42, v42
	v_exp_f32_e32 v43, v43
	v_exp_f32_e32 v44, v44
	v_exp_f32_e32 v45, v45
	v_exp_f32_e32 v46, v46
	v_exp_f32_e32 v47, v47
	v_add_f32_e32 v48, v51, v48
	v_add_f32_e32 v48, v102, v48
	v_add_f32_e32 v48, v103, v48
	v_add_f32_e32 v48, v108, v48
	v_cvt_pk_bf16_f32 v32, v49, v50
	v_cvt_pk_bf16_f32 v33, v51, v102
	v_cvt_pk_bf16_f32 v34, v103, v108
	v_cvt_pk_bf16_f32 v35, v109, v110
	v_mfma_f32_32x32x16_bf16 v[16:31], v[116:119], v[52:55], v[16:31]
	v_cvt_pk_bf16_f32 v36, v40, v41
	v_cvt_pk_bf16_f32 v37, v42, v43
	v_cvt_pk_bf16_f32 v38, v44, v45
	v_cvt_pk_bf16_f32 v39, v46, v47
	v_add_f32_e32 v48, v109, v48
	v_add_f32_e32 v48, v110, v48
	v_add_f32_e32 v40, v40, v48
	v_mfma_f32_32x32x16_bf16 v[0:15], v[120:123], v[52:55], v[0:15]
	v_add_f32_e32 v40, v41, v40
	v_add_f32_e32 v40, v42, v40
	v_add_f32_e32 v40, v43, v40
	v_add_f32_e32 v40, v44, v40
	v_add_f32_e32 v40, v45, v40
	v_add_f32_e32 v40, v46, v40
	s_waitcnt lgkmcnt(0)
	s_nop 0
	v_mfma_f32_32x32x16_bf16 v[16:31], v[56:59], v[32:35], v[16:31]
	v_mfma_f32_32x32x16_bf16 v[0:15], v[60:63], v[32:35], v[0:15]
	v_add_f32_e32 v32, v47, v40
	v_add_f32_e32 v100, v100, v32
	v_cmp_lt_f32_e32 vcc, s34, v32
	v_mfma_f32_32x32x16_bf16 v[16:31], v[124:127], v[36:39], v[16:31]
	v_mfma_f32_32x32x16_bf16 v[0:15], v[128:131], v[36:39], v[0:15]
	s_cbranch_vccz .Lmb_532b
	ds_bpermute_b32 v33, v93, v32
	s_waitcnt lgkmcnt(0)
	v_add_f32_e32 v32, v32, v33
	v_log_f32_e32 v33, v32
	v_cmp_lt_f32_e32 vcc, s34, v32
	v_floor_f32_e32 v33, v33
	s_nop 0
	v_cndmask_b32_e32 v33, 0, v33, vcc
	v_exp_f32_e64 v32, -v33
	v_add_f32_e32 v101, v101, v33
	v_mul_f32_e32 v100, v100, v32
	v_pk_mul_f32 v[30:31], v[30:31], v[32:33] op_sel_hi:[1,0]
	v_pk_mul_f32 v[28:29], v[28:29], v[32:33] op_sel_hi:[1,0]
	v_pk_mul_f32 v[26:27], v[26:27], v[32:33] op_sel_hi:[1,0]
	v_pk_mul_f32 v[24:25], v[24:25], v[32:33] op_sel_hi:[1,0]
	v_pk_mul_f32 v[22:23], v[22:23], v[32:33] op_sel_hi:[1,0]
	v_pk_mul_f32 v[20:21], v[20:21], v[32:33] op_sel_hi:[1,0]
	v_pk_mul_f32 v[18:19], v[18:19], v[32:33] op_sel_hi:[1,0]
	v_pk_mul_f32 v[16:17], v[16:17], v[32:33] op_sel_hi:[1,0]
	v_pk_mul_f32 v[14:15], v[14:15], v[32:33] op_sel_hi:[1,0]
	v_pk_mul_f32 v[12:13], v[12:13], v[32:33] op_sel_hi:[1,0]
	v_pk_mul_f32 v[10:11], v[10:11], v[32:33] op_sel_hi:[1,0]
	v_pk_mul_f32 v[8:9], v[8:9], v[32:33] op_sel_hi:[1,0]
	v_pk_mul_f32 v[6:7], v[6:7], v[32:33] op_sel_hi:[1,0]
	v_pk_mul_f32 v[4:5], v[4:5], v[32:33] op_sel_hi:[1,0]
	v_pk_mul_f32 v[2:3], v[2:3], v[32:33] op_sel_hi:[1,0]
	v_pk_mul_f32 v[0:1], v[0:1], v[32:33] op_sel_hi:[1,0]
	s_branch .Lmb_532b
